# A work queue: next item's queue atomic issued by thread 0 inside the current item's epilogue (late prefetch), head only waits and publishes it
# baseline (speedup 1.0000x reference)
; template <int DQK, int DV, int MODE> ...
;     ...
;   if (MODE == 0) { wkb = max(kt_begin, w >> 1); wke = (w * 32 + 159) / 64 + 1; }
;   else { wkb = 0; wke = (qpos0 + w * 32 + 31) / 64 + 1; }
;   u32x4 rk[NKC], rv[NVC];
;   auto gload = [&](int kt) {
; #pragma unroll
;     for (int i = 0; i < NKC; ++i) { const int c = tid + 256 * i, key = c / KCH, part = c % KCH; rk[i] = *(const u32x4*)(Kp + (unsigned)((kt * 64 + key) * krs + part * 8)); }
;     if (MODE == 0) {
; #pragma unroll
;       for (int i = 0; i < NVC; ++i) { const int c = tid + 256 * i, key = c >> 3, part = c & 7; rv[i] = *(const u32x4*)(Vp + (unsigned)((kt * 64 + key) * vrs + part * 8)); }
;     } else {
; #pragma unroll
;       for (int i = 0; i < NVC; ++i) { const int c = tid + 256 * i, dv = c >> 3, kc = c & 7; rv[i] = *(const u32x4*)(Vp + (unsigned)(dv * vrs + kt * 64 + kc * 8)); }
;     }
;   };
;   auto sstore = [&]() {
; #pragma unroll
;     for (int i = 0; i < NKC; ++i) { const int c = tid + 256 * i, key = c / KCH, part = c % KCH; *(u32x4*)(Ks + key * KST + part * 8) = rk[i]; }
;     if (MODE == 0) {
; #pragma unroll
;       for (int i = 0; i < NVC; ++i) {
;         const int c = tid + 256 * i, key = c >> 3, part = c & 7;
;         const int pos = (key & 32) + ((key >> 2) & 3) * 8 + ((key >> 4) & 1) * 4 + (key & 3);
;     ...
;     const int a = next_item(p.counters + ((cset * 4 + l) * 3 + 2) * 8, s_item, tid);
.LBB0_579:
	v_add_u32_e32 v0, 0x9f, v212
	v_ashrrev_i32_e32 v2, 31, v0
	v_lshrrev_b32_e32 v2, 26, v2
	v_add_u32_e32 v0, v0, v2
	v_ashrrev_i32_e32 v89, 6, v0
	v_lshrrev_b32_e32 v0, 2, v122
	v_and_b32_e32 v0, 24, v0
	v_lshrrev_b32_e32 v2, 5, v122
	v_and_or_b32 v0, v2, 4, v0
	v_lshrrev_b32_e32 v2, 3, v122
	s_movk_i32 s0, 0x81
	v_and_b32_e32 v2, 35, v2
	v_cmp_gt_i32_e64 s[0:1], s0, v122
	v_or_b32_e32 v3, v0, v2
	v_mul_u32_u24_e32 v4, 0x50, v203
	v_bitop3_b32 v0, v0, 32, v2 bitop3:0x36
	v_writelane_b32 v254, s0, 44
	v_lshlrev_b32_e32 v4, 1, v4
	v_lshlrev_b32_e32 v0, 1, v0
	v_writelane_b32 v254, s1, 45
	v_add3_u32 v101, 0, v0, v4
	v_cmp_eq_u32_e64 s[0:1], 0, v211
	v_max_i32_e32 v0, 0xffffff81, v122
	v_sub_u32_e32 v0, v0, v122
	v_writelane_b32 v254, s0, 46
	v_add_u32_e32 v0, 0xff, v0
	v_lshrrev_b32_e32 v2, 8, v0
	v_writelane_b32 v254, s1, 47
	s_movk_i32 s0, 0x1900
	v_cmp_gt_u32_e64 s[0:1], s0, v0
	v_add_u32_e32 v2, 1, v2
	v_and_b32_e32 v103, 0x1fffffe, v2
	v_writelane_b32 v254, s0, 48
	v_and_b32_e32 v102, 0xffffff00, v0
	s_waitcnt vmcnt(0)
	v_or_b32_e32 v84, 16, v134
	v_writelane_b32 v254, s1, 49
	s_movk_i32 s0, 0x18ff
	v_cmp_lt_u32_e64 s[0:1], s0, v0
	v_lshlrev_b32_e32 v0, 7, v210
	v_lshlrev_b32_e32 v3, 1, v3
	v_writelane_b32 v254, s0, 50
	v_ashrrev_i32_e32 v87, 7, v122
	v_add3_u32 v100, 0, v3, v4
	v_writelane_b32 v254, s1, 51
	v_cmp_ne_u32_e64 s[0:1], v2, v103
	v_lshlrev_b32_e32 v2, 4, v211
	v_sub_u32_e32 v106, v0, v2
	v_add_u32_e32 v0, v212, v209
	v_sub_u32_e32 v107, v0, v132
	v_lshlrev_b32_e32 v0, 6, v133
	v_sub_u32_e32 v0, v213, v0
	v_writelane_b32 v254, s0, 52
	v_add_u32_e32 v86, 0x800, v0
	v_lshlrev_b32_e32 v0, 6, v131
	v_ashrrev_i32_e32 v135, 31, v134
	v_ashrrev_i32_e32 v85, 31, v84
	v_lshl_add_u32 v104, v103, 8, v122
	v_writelane_b32 v254, s1, 53
	v_lshl_add_u32 v105, v209, 2, 0
	v_add_u32_e32 v108, 64, v204
	v_add_u32_e32 v109, 64, v202
	v_add_u32_e32 v110, 64, v133
	v_sub_u32_e32 v88, v213, v0
	v_add_u32_e32 v111, 64, v131
	s_mov_b64 s[0:1], exec
	v_readlane_b32 s2, v254, 40
	v_readlane_b32 s3, v254, 41
	s_and_b64 s[2:3], s[0:1], s[2:3]
	s_mov_b64 exec, s[2:3]
	s_cbranch_execz .Lpf_A_first
	v_mov_b32_e32 v249, 1
	v_readlane_b32 s4, v254, 42
	v_readlane_b32 s5, v254, 43
	s_nop 4
	global_atomic_add v249, v1, v249, s[4:5] offset:64 sc0
.Lpf_A_first:
	s_mov_b64 exec, s[0:1]
	s_branch .LBB0_582

; __device__ __forceinline__ int next_item(int* counter, int* s_item, const int tid) {
;   __syncthreads();
;   if (tid == 0) *s_item = atomicAdd(counter, 1);
;   __syncthreads();
;   return *s_item;
; }
;     ...
;     const int a = next_item(p.counters + ((cset * 4 + l) * 3 + 2) * 8, s_item, tid);
;     if (a >= 2304) break;
.LBB0_582:
	s_waitcnt lgkmcnt(0)
	s_barrier
	s_mov_b64 s[0:1], exec
	v_readlane_b32 s2, v254, 40
	v_readlane_b32 s3, v254, 41
	s_and_b64 s[2:3], s[0:1], s[2:3]
	s_mov_b64 exec, s[2:3]
	s_cbranch_execz .LBB0_586
	s_waitcnt vmcnt(0)
	ds_write_b32 v1, v249 offset:43008
	v_mov_b32_e32 v249, 0x7fffffff

; __device__ __forceinline__ void store4bf(bf16_t* p, f32x4 v) { u32x2 o; o.x = pack2(v[0], v[1]); o.y = pack2(v[2], v[3]); *(u32x2*)p = o; }
; template <int DQK, int DV, int MODE> ...
;     ...
;   for (int qi = 0; qi < 2; ++qi) lrow[qi] = xsum_rows(lrow[qi]);
;     ...
; #pragma unroll
;     for (int qi = 0; qi < 2; ++qi) {
;       const float inv = 1.f / lr[qi];
;       const long tok = row_q0 + (long)(w * 32 + qi * 16 + fr) * d;
; #pragma unroll
;       for (int dt = 0; dt < 4; ++dt) store4bf(p.oA + ((size_t)g * T_TOK + tok) * 384 + h * 64 + dt * 16 + fq * 4, O[qi][dt] * inv);
;       if (fq == 0) p.lseA[((size_t)g * T_TOK + tok) * 6 + h] = (mr[qi] + __log2f(lr[qi])) * LN2;
;     }
.LBB0_735:
	v_mov_b32_e32 v0, v119
	s_nop 1
	v_permlane16_swap_b32_e32 v119, v0
	v_add_f32_e32 v0, v119, v0
	v_mov_b32_e32 v2, v0
	s_nop 1
	v_permlane32_swap_b32_e32 v0, v2
	s_waitcnt vmcnt(2)
	v_add_f32_e32 v24, v0, v2
	v_readlane_b32 s0, v254, 57
	v_div_scale_f32 v20, s[4:5], v24, v24, 1.0
	v_readlane_b32 s1, v254, 58
	v_rcp_f32_e32 v21, v20
	v_mov_b32_e32 v0, v117
	s_and_b64 s[0:1], s[0:1], exec
	s_nop 0
	v_permlane16_swap_b32_e32 v117, v0
	v_readlane_b32 s0, v254, 59
	v_readlane_b32 s3, v254, 56
	v_add_f32_e32 v22, v117, v0
	v_readlane_b32 s1, v254, 60
	v_mov_b32_e32 v0, s3
	s_cselect_b32 s2, 2, 4
	s_and_b64 s[0:1], s[0:1], exec
	v_bfe_i32 v2, v0, 0, 8
	v_fma_f32 v0, -v20, v21, 1.0
	v_readlane_b32 s0, v254, 54
	v_fmac_f32_e32 v21, v0, v21
	v_div_scale_f32 v0, vcc, 1.0, v24, 1.0
	v_readlane_b32 s1, v254, 55
	v_mul_f32_e32 v25, v0, v21
	s_cselect_b32 s2, 0, s2
	s_ashr_i32 s1, s0, 31
	v_fma_f32 v26, -v20, v25, v0
	s_lshl_b64 s[0:1], s[0:1], 14
	v_fmac_f32_e32 v25, v26, v21
	v_readlane_b32 s9, v254, 62
	v_fma_f32 v0, -v20, v25, v0
	s_add_u32 s4, s9, s0
	v_readlane_b32 s8, v254, 61
	v_readlane_b32 s76, v254, 13
	v_div_fmas_f32 v0, v0, v21, v25
	v_lshlrev_b64 v[20:21], s2, v[134:135]
	s_addc_u32 s5, s8, s1
	v_readlane_b32 s86, v254, 23
	v_readlane_b32 s87, v254, 24
	v_lshl_add_u64 v[20:21], s[4:5], 0, v[20:21]
	s_movk_i32 s3, 0x300
	s_waitcnt vmcnt(1)
	v_mov_b64_e32 v[28:29], s[86:87]
	v_mad_u64_u32 v[28:29], s[4:5], v20, s3, v[28:29]
	v_div_fixup_f32 v26, v0, v24, 1.0
	v_mov_b32_e32 v0, v29
	v_mad_u64_u32 v[30:31], s[4:5], v21, s3, v[0:1]
	v_readlane_b32 s10, v254, 63
	v_mov_b32_e32 v29, v30
	v_readlane_b32 s11, v255, 0
	v_lshlrev_b32_e32 v0, 1, v132
	s_waitcnt vmcnt(0)
	s_mov_b64 vcc, exec
	v_readlane_b32 s4, v254, 40
	v_readlane_b32 s5, v254, 41
	s_and_b64 s[4:5], vcc, s[4:5]
	s_mov_b64 exec, s[4:5]
	s_cbranch_execz .Lpf_A_epi
	v_mov_b32_e32 v249, 1
	v_readlane_b32 s4, v254, 42
	v_readlane_b32 s5, v254, 43
	s_nop 4
	global_atomic_add v249, v1, v249, s[4:5] offset:64 sc0
.Lpf_A_epi:
	s_mov_b64 exec, vcc
	v_pk_mul_f32 v[32:33], v[48:49], v[26:27] op_sel_hi:[1,0]
	v_lshl_add_u64 v[28:29], s[10:11], 1, v[28:29]
	v_lshl_add_u64 v[28:29], v[28:29], 0, v[0:1]
	v_pk_mul_f32 v[30:31], v[50:51], v[26:27] op_sel_hi:[1,0]
	v_cvt_pk_bf16_f32 v32, v32, v33
	v_mov_b32_e32 v23, v22
	v_cvt_pk_bf16_f32 v33, v30, v31
	global_store_dwordx2 v[28:29], v[32:33], off
	v_pk_mul_f32 v[32:33], v[44:45], v[26:27] op_sel_hi:[1,0]
	v_pk_mul_f32 v[30:31], v[46:47], v[26:27] op_sel_hi:[1,0]
	v_cvt_pk_bf16_f32 v32, v32, v33
	v_permlane32_swap_b32_e32 v22, v23
	v_cvt_pk_bf16_f32 v33, v30, v31
	global_store_dwordx2 v[28:29], v[32:33], off offset:32
	v_pk_mul_f32 v[30:31], v[42:43], v[26:27] op_sel_hi:[1,0]
	v_pk_mul_f32 v[32:33], v[40:41], v[26:27] op_sel_hi:[1,0]
	v_ashrrev_i32_e32 v3, 31, v2
	v_readlane_b32 s77, v254, 14
	v_readlane_b32 s78, v254, 15
	v_readlane_b32 s79, v254, 16
	v_readlane_b32 s80, v254, 17
	v_readlane_b32 s81, v254, 18
	v_readlane_b32 s82, v254, 19
	v_readlane_b32 s83, v254, 20
	v_readlane_b32 s84, v254, 21
	v_readlane_b32 s85, v254, 22
	v_readlane_b32 s88, v254, 25
	v_readlane_b32 s89, v254, 26
	v_readlane_b32 s90, v254, 27
	v_readlane_b32 s91, v254, 28
	v_cvt_pk_bf16_f32 v32, v32, v33
	v_cvt_pk_bf16_f32 v33, v30, v31
	v_pk_mul_f32 v[30:31], v[38:39], v[26:27] op_sel_hi:[1,0]
	v_pk_mul_f32 v[26:27], v[36:37], v[26:27] op_sel_hi:[1,0]
	global_store_dwordx2 v[28:29], v[32:33], off offset:64
	v_cvt_pk_bf16_f32 v26, v26, v27
	v_cvt_pk_bf16_f32 v27, v30, v31
	global_store_dwordx2 v[28:29], v[26:27], off offset:96
	s_mov_b64 s[4:5], exec
	v_readlane_b32 s6, v254, 46
	v_readlane_b32 s7, v254, 47
	v_readlane_b32 s56, v254, 31
	s_and_b64 s[6:7], s[4:5], s[6:7]
	v_readlane_b32 s52, v254, 29
	s_mov_b32 s72, s56
	v_readlane_b32 s42, v254, 33
	v_readlane_b32 s43, v254, 34
	v_readlane_b32 s44, v254, 35
	v_readlane_b32 s53, v254, 30
	v_readlane_b32 s57, v254, 32
	s_mov_b64 exec, s[6:7]
	s_cbranch_execz .LBB0_737
	v_log_f32_e32 v26, v24
	v_mad_u64_u32 v[24:25], s[6:7], v20, 24, s[90:91]
	v_mov_b32_e32 v20, v25
	v_add_f32_e32 v25, v121, v26
	v_mad_u64_u32 v[20:21], s[6:7], v21, 24, v[20:21]
	v_mul_f32_e32 v26, 0x3f317218, v25
	v_mov_b32_e32 v25, v20
	v_lshl_add_u64 v[20:21], v[2:3], 2, v[24:25]
	global_store_dword v[20:21], v26, off
